# prompt attention: selected pass first K/V tile (block 0, always selected) requested right after the compressed pass so it lands during the top-k ranking
# speedup vs baseline: 1.0090x; 1.0090x over previous
; #define LAS __attribute__((address_space(3)))
; __device__ __forceinline__ void nsa_prompt_unit(Frame& F, int l, int b, int kvh, int c) {
;     ...
;     __syncthreads();
;     tile_dma((const bf16_t*)(F.ws + WS_KCP) + (size_t)(b * 4 + kvh) * 4096, (const bf16_t*)(F.ws + WS_VCTP) + (size_t)(b * 4 + kvh) * 4096, F.lds, w, lane);
;     bf16x8 qf[4];
; #pragma unroll
;     for (int ks = 0; ks < 4; ++ks) qf[ks] = *(const bf16x8*)(P + (size_t)tok * NPROJ + C_Q + head * 64 + 16 * ks + 8 * h);
;     const float* gt = (const float*)(F.ws + WS_GATE) + (size_t)tok * 64 + head * 3;
;     const float g_cmp = gt[0], g_sel = gt[1], g_win = gt[2];
;     LAS f32x4* ltot = (LAS f32x4*)(F.lds + AL_TOT) + tid;
;     FlashState S;
;     {
;         if (tid < 128) msk[tid] = 0u; if (tid < 2) uni[tid] = 0u;
;         __syncthreads();
;         flash_reset(S);
;         f32x16 s0, s1; flash_scores(kbuf, qf, r, h, 0.f, s0, s1);
;         const int nvalid = c + (qloc == 63 ? 1 : 0);
;         bf16x8 vf[8]; flash_vload(vbuf, r, h, vf);
;         flash_first(S, s0, s1, 0, nvalid - 1, h, true);
.LBB0_793:
	s_and_b64 s[22:23], s[44:45], exec
	v_mov_b32_e32 v82, v0
	s_cselect_b32 s8, s93, s92
	s_mov_b32 m0, s82
	v_and_b32_e32 v83, 63, v82
	v_bfe_u32 v1, v82, 2, 3
	s_lshl_b32 s4, s8, 6
	v_lshlrev_b32_e32 v2, 4, v83
	s_add_i32 s36, s82, 0x2000
	v_and_b32_e32 v68, 3, v82
	v_or_b32_e32 v1, s15, v1
	s_or_b32 s4, s4, s16
	s_barrier
	global_load_lds_dwordx4 v2, s[54:55]
	s_mov_b32 m0, s36
	v_add_u32_e32 v128, s4, v1
	v_or_b32_e32 v84, s17, v68
	global_load_lds_dwordx4 v2, s[56:57]
	v_mov_b64_e32 v[2:3], s[20:21]
	v_bfe_u32 v66, v82, 5, 1
	v_mad_i64_i32 v[130:131], s[22:23], v128, s87, v[2:3]
	v_lshlrev_b32_e32 v98, 7, v84
	v_lshl_add_u64 v[2:3], v[130:131], 0, v[98:99]
	v_lshlrev_b32_e32 v98, 4, v66
	v_lshl_add_u64 v[2:3], v[2:3], 0, v[98:99]
	v_lshl_add_u64 v[4:5], v[2:3], 0, s[96:97]
	v_add_co_u32_e32 v2, vcc, s11, v2
	v_ashrrev_i32_e32 v129, 31, v128
	s_nop 0
	v_addc_co_u32_e32 v3, vcc, 0, v3, vcc
	global_load_dwordx4 v[100:103], v[4:5], off offset:32
	global_load_dwordx4 v[104:107], v[4:5], off offset:64
	global_load_dwordx4 v[108:111], v[2:3], off
	global_load_dwordx4 v[112:115], v[4:5], off offset:96
	v_lshlrev_b64 v[2:3], 8, v[128:129]
	v_mul_u32_u24_e32 v4, 3, v84
	v_lshl_add_u64 v[2:3], s[50:51], 0, v[2:3]
	v_lshlrev_b32_e32 v98, 2, v4
	v_lshl_add_u64 v[2:3], v[2:3], 0, v[98:99]
	global_load_dwordx3 v[124:126], v[2:3], off
	v_cmp_gt_i32_e32 vcc, s86, v82
	v_lshl_add_u32 v2, v82, 2, 0
	s_and_saveexec_b64 s[22:23], vcc
	v_add_u32_e32 v3, 0x10000, v2
	ds_write_b32 v3, v99
	s_or_b64 exec, exec, s[22:23]
	v_cmp_gt_i32_e32 vcc, 2, v82
	s_and_saveexec_b64 s[22:23], vcc
	v_add_u32_e32 v2, 0x10200, v2
	ds_write_b32 v2, v99
	s_or_b64 exec, exec, s[22:23]
	v_and_b32_e32 v2, 31, v82
	v_lshlrev_b32_e32 v2, 4, v2
	v_lshlrev_b32_e32 v3, 10, v66
	v_add3_u32 v127, 0, v2, v3
	s_waitcnt vmcnt(0) lgkmcnt(0)
	s_barrier
	ds_read_b128 v[2:5], v127
	ds_read_b128 v[6:9], v127 offset:512
	ds_read_b128 v[34:37], v127 offset:2048
	ds_read_b128 v[38:41], v127 offset:2560
	ds_read_b128 v[42:45], v127 offset:4096
	ds_read_b128 v[46:49], v127 offset:4608
	ds_read_b128 v[50:53], v127 offset:6144
	ds_read_b128 v[54:57], v127 offset:6656
	s_waitcnt lgkmcnt(7)
	v_mfma_f32_32x32x16_bf16 v[18:33], v[2:5], v[108:111], 0
	v_cmp_eq_u32_e32 vcc, 63, v1
	v_mov_b32_e32 v67, s8
	s_nop 0
	v_addc_co_u32_e64 v69, s[42:43], 0, v67, vcc
	s_waitcnt lgkmcnt(6)
	v_mfma_f32_32x32x16_bf16 v[2:17], v[6:9], v[108:111], 0
	s_waitcnt lgkmcnt(5)
	v_mfma_f32_32x32x16_bf16 v[18:33], v[34:37], v[100:103], v[18:33]
	s_waitcnt lgkmcnt(4)
	v_mfma_f32_32x32x16_bf16 v[2:17], v[38:41], v[100:103], v[2:17]
	s_waitcnt lgkmcnt(3)
	v_mfma_f32_32x32x16_bf16 v[18:33], v[42:45], v[104:107], v[18:33]
	s_waitcnt lgkmcnt(2)
	v_mfma_f32_32x32x16_bf16 v[2:17], v[46:49], v[104:107], v[2:17]
	s_waitcnt lgkmcnt(1)
	v_mfma_f32_32x32x16_bf16 v[18:33], v[50:53], v[112:115], v[18:33]
	s_waitcnt lgkmcnt(0)
	v_mfma_f32_32x32x16_bf16 v[2:17], v[54:57], v[112:115], v[2:17]
	ds_read_b128 v[62:65], v127 offset:8192
	ds_read_b128 v[34:37], v127 offset:8704
	ds_read_b128 v[58:61], v127 offset:10240
	ds_read_b128 v[38:41], v127 offset:10752
	ds_read_b128 v[54:57], v127 offset:12288
	ds_read_b128 v[42:45], v127 offset:12800
	ds_read_b128 v[50:53], v127 offset:14336
	ds_read_b128 v[46:49], v127 offset:14848
	v_addc_co_u32_e32 v67, vcc, -1, v67, vcc
	v_lshlrev_b32_e32 v138, 2, v66
	v_cmp_lt_u32_e32 vcc, v138, v69
	v_or_b32_e32 v139, 32, v138
	v_or_b32_e32 v140, 33, v138
	v_cndmask_b32_e32 v18, v233, v18, vcc
	v_cmp_lt_u32_e32 vcc, v139, v69
	v_or_b32_e32 v141, 2, v138
	v_or_b32_e32 v142, 34, v138
	v_cndmask_b32_e32 v2, v233, v2, vcc
	v_cmp_lt_i32_e32 vcc, v138, v67
	v_or_b32_e32 v143, 3, v138
	v_or_b32_e32 v144, 35, v138
	v_cndmask_b32_e32 v19, v233, v19, vcc
	v_cmp_lt_u32_e32 vcc, v140, v69
	v_or_b32_e32 v145, 8, v138
	v_or_b32_e32 v146, 40, v138
	v_cndmask_b32_e32 v3, v233, v3, vcc
	v_cmp_lt_u32_e32 vcc, v141, v69
	v_or_b32_e32 v147, 9, v138
	v_or_b32_e32 v148, 41, v138
	v_cndmask_b32_e32 v20, v233, v20, vcc
	v_cmp_lt_u32_e32 vcc, v142, v69
	v_or_b32_e32 v149, 10, v138
	v_or_b32_e32 v150, 42, v138
	v_cndmask_b32_e32 v4, v233, v4, vcc
	v_cmp_lt_u32_e32 vcc, v143, v69
	v_or_b32_e32 v151, 11, v138
	v_or_b32_e32 v152, 43, v138
	v_cndmask_b32_e32 v21, v233, v21, vcc
	v_cmp_lt_u32_e32 vcc, v144, v69
	v_or_b32_e32 v153, 16, v138
	v_or_b32_e32 v154, 48, v138
	v_cndmask_b32_e32 v5, v233, v5, vcc
	v_cmp_lt_u32_e32 vcc, v145, v69
	v_or_b32_e32 v155, 17, v138
	v_or_b32_e32 v156, 49, v138
	v_cndmask_b32_e32 v66, v233, v22, vcc
	v_cmp_lt_u32_e32 vcc, v146, v69
	v_or_b32_e32 v157, 18, v138
	v_or_b32_e32 v158, 50, v138
	v_cndmask_b32_e32 v6, v233, v6, vcc
	v_cmp_lt_u32_e32 vcc, v147, v69
	v_or_b32_e32 v159, 19, v138
	v_or_b32_e32 v160, 51, v138
	v_cndmask_b32_e32 v70, v233, v23, vcc
	v_cmp_lt_u32_e32 vcc, v148, v69
	v_or_b32_e32 v161, 24, v138
	v_or_b32_e32 v162, 56, v138
	v_cndmask_b32_e32 v7, v233, v7, vcc
	v_cmp_lt_u32_e32 vcc, v149, v69
	v_or_b32_e32 v163, 25, v138
	v_or_b32_e32 v164, 57, v138
	v_cndmask_b32_e32 v71, v233, v24, vcc
	v_cmp_lt_u32_e32 vcc, v150, v69
	v_or_b32_e32 v165, 26, v138
	v_or_b32_e32 v166, 58, v138
	v_cndmask_b32_e32 v8, v233, v8, vcc
	v_cmp_lt_u32_e32 vcc, v151, v69
	v_or_b32_e32 v167, 27, v138
	v_or_b32_e32 v168, 59, v138
	v_cndmask_b32_e32 v72, v233, v25, vcc
	v_cmp_lt_u32_e32 vcc, v152, v69
	s_movk_i32 s4, 0x104
	s_nop 0
	v_cndmask_b32_e32 v9, v233, v9, vcc
	v_cmp_lt_u32_e32 vcc, v153, v69
	s_nop 1
	v_cndmask_b32_e32 v26, v233, v26, vcc
	v_cmp_lt_u32_e32 vcc, v154, v69
	s_nop 1
	v_cndmask_b32_e32 v73, v233, v10, vcc
	v_max3_f32 v10, v233, v18, v2
	v_cmp_lt_u32_e32 vcc, v155, v69
	v_max3_f32 v10, v10, v19, v3
; __device__ __forceinline__ void flash_mask(f32x16& s0, f32x16& s1, int lo, int hi, int h) {
; #pragma unroll
;     for (int i = 0; i < 16; ++i) { const int key = (i & 3) + 8 * (i >> 2) + 4 * h;
;         s0[i] = (key >= lo && key <= hi) ? s0[i] : -INFINITY; s1[i] = (key + 32 >= lo && key + 32 <= hi) ? s1[i] : -INFINITY; }
; }
; __device__ __forceinline__ float flash_rowmax(const f32x16& s0, const f32x16& s1) {
;     float mx = -INFINITY;
; #pragma unroll
;     for (int i = 0; i < 16; ++i) asm("v_max3_f32 %0, %1, %2, %3" : "=v"(mx) : "v"(mx), "v"(s0[i]), "v"(s1[i]));
;     return xhalf_max(mx);
; }
; __device__ __forceinline__ void flash_first(FlashState& S, f32x16& s0, f32x16& s1, int lo, int hi, int h, bool masked) {
;     if (masked) flash_mask(s0, s1, lo, hi, h);
;     S.m = fmaxf(flash_rowmax(s0, s1), NEG_BIG);
;     float ls = 0.f;
; #pragma unroll
;     for (int i = 0; i < 16; ++i) { s0[i] = __builtin_amdgcn_exp2f(s0[i] - S.m); s1[i] = __builtin_amdgcn_exp2f(s1[i] - S.m); ls += s0[i] + s1[i]; }
;     S.l = ls;
	s_nop 0
	v_max3_f32 v10, v10, v20, v4
	s_nop 0
	v_cndmask_b32_e32 v74, v233, v27, vcc
	v_cmp_lt_u32_e32 vcc, v156, v69
	v_max3_f32 v10, v10, v21, v5
	s_nop 0
	v_max3_f32 v10, v10, v66, v6
	s_nop 0
	v_cndmask_b32_e32 v75, v233, v11, vcc
	v_cmp_lt_u32_e32 vcc, v157, v69
	v_max3_f32 v10, v10, v70, v7
	s_nop 0
	v_max3_f32 v10, v10, v71, v8
	s_nop 0
	v_cndmask_b32_e32 v76, v233, v28, vcc
	v_cmp_lt_u32_e32 vcc, v158, v69
	v_max3_f32 v10, v10, v72, v9
	s_nop 0
	v_max3_f32 v10, v10, v26, v73
	s_nop 0
	v_cndmask_b32_e32 v12, v233, v12, vcc
	v_cmp_lt_u32_e32 vcc, v159, v69
	v_max3_f32 v10, v10, v74, v75
	s_nop 0
	v_max3_f32 v10, v10, v76, v12
	s_nop 0
	v_cndmask_b32_e32 v77, v233, v29, vcc
	v_cmp_lt_u32_e32 vcc, v160, v69
	s_nop 1
	v_cndmask_b32_e32 v78, v233, v13, vcc
	v_cmp_lt_u32_e32 vcc, v161, v69
	v_max3_f32 v10, v10, v77, v78
	s_nop 1
	v_cndmask_b32_e32 v79, v233, v30, vcc
	v_cmp_lt_u32_e32 vcc, v162, v69
	s_nop 1
	v_cndmask_b32_e32 v80, v233, v14, vcc
	v_cmp_lt_u32_e32 vcc, v163, v69
	v_max3_f32 v10, v10, v79, v80
	s_nop 1
	v_cndmask_b32_e32 v81, v233, v31, vcc
	v_cmp_lt_u32_e32 vcc, v164, v69
	s_nop 1
	v_cndmask_b32_e32 v85, v233, v15, vcc
	v_cmp_lt_u32_e32 vcc, v165, v69
	v_max3_f32 v10, v10, v81, v85
	s_nop 1
	v_cndmask_b32_e32 v86, v233, v32, vcc
	v_cmp_lt_u32_e32 vcc, v166, v69
	s_nop 1
	v_cndmask_b32_e32 v16, v233, v16, vcc
	v_cmp_lt_u32_e32 vcc, v167, v69
	v_max3_f32 v10, v10, v86, v16
	s_nop 1
	v_cndmask_b32_e32 v87, v233, v33, vcc
	v_cmp_lt_u32_e32 vcc, v168, v69
	s_nop 1
	v_cndmask_b32_e32 v17, v233, v17, vcc
	v_max3_f32 v10, v10, v87, v17
	s_nop 0
	v_mov_b32_e32 v11, v10
	s_nop 1
	v_permlane32_swap_b32_e32 v10, v11
	v_max3_f32 v69, v10, v11, s12
	v_sub_f32_e32 v2, v2, v69
	v_exp_f32_e32 v22, v2
	v_sub_f32_e32 v2, v19, v69
	v_exp_f32_e32 v11, v2
	v_sub_f32_e32 v2, v3, v69
	v_exp_f32_e32 v23, v2
	v_sub_f32_e32 v2, v20, v69
	v_exp_f32_e32 v20, v2
	v_sub_f32_e32 v2, v4, v69
	v_exp_f32_e32 v24, v2
	v_sub_f32_e32 v2, v21, v69
	v_exp_f32_e32 v21, v2
	v_sub_f32_e32 v2, v5, v69
	v_exp_f32_e32 v25, v2
	v_sub_f32_e32 v2, v66, v69
	v_exp_f32_e32 v29, v2
	v_sub_f32_e32 v2, v6, v69
	v_exp_f32_e32 v67, v2
	v_sub_f32_e32 v2, v70, v69
	v_exp_f32_e32 v28, v2
	v_sub_f32_e32 v2, v7, v69
	v_exp_f32_e32 v66, v2
	v_sub_f32_e32 v2, v71, v69
	v_exp_f32_e32 v31, v2
	v_sub_f32_e32 v2, v8, v69
	v_exp_f32_e32 v33, v2
	v_sub_f32_e32 v2, v72, v69
	v_exp_f32_e32 v30, v2
	v_sub_f32_e32 v2, v9, v69
	v_exp_f32_e32 v32, v2
	v_sub_f32_e32 v2, v26, v69
	v_exp_f32_e32 v19, v2
	v_sub_f32_e32 v2, v73, v69
	v_exp_f32_e32 v27, v2
	v_sub_f32_e32 v2, v74, v69
	v_sub_f32_e32 v10, v18, v69
	v_exp_f32_e32 v18, v2
	v_sub_f32_e32 v2, v75, v69
	v_exp_f32_e32 v26, v2
	v_sub_f32_e32 v2, v76, v69
	v_exp_f32_e32 v13, v2
	v_sub_f32_e32 v2, v12, v69
	v_exp_f32_e32 v15, v2
	v_sub_f32_e32 v2, v77, v69
	v_exp_f32_e32 v12, v2
	v_sub_f32_e32 v2, v78, v69
	v_exp_f32_e32 v10, v10
	v_exp_f32_e32 v14, v2
	v_sub_f32_e32 v2, v79, v69
	v_exp_f32_e32 v7, v2
	v_sub_f32_e32 v2, v80, v69
	v_exp_f32_e32 v9, v2
	v_sub_f32_e32 v2, v81, v69
	v_exp_f32_e32 v6, v2
	v_sub_f32_e32 v2, v85, v69
	v_exp_f32_e32 v8, v2
	v_sub_f32_e32 v2, v86, v69
	v_add_f32_e32 v81, v22, v10
	v_exp_f32_e32 v3, v2
	v_sub_f32_e32 v2, v16, v69
	v_add_f32_e32 v81, 0, v81
	v_add_f32_e32 v85, v23, v11
	v_exp_f32_e32 v5, v2
	v_sub_f32_e32 v2, v87, v69
	v_sub_f32_e32 v4, v17, v69
	v_add_f32_e32 v69, v24, v20
	v_add_f32_e32 v81, v85, v81
	v_add_f32_e32 v80, v25, v21
	v_add_f32_e32 v69, v69, v81
	v_pk_add_f32 v[78:79], v[66:67], v[28:29]
	v_add_f32_e32 v69, v80, v69
	v_add_f32_e32 v69, v79, v69
	v_pk_add_f32 v[76:77], v[32:33], v[30:31]
	v_add_f32_e32 v69, v78, v69
	v_add_f32_e32 v69, v77, v69
	v_pk_add_f32 v[74:75], v[26:27], v[18:19]
	v_add_f32_e32 v69, v76, v69
	v_add_f32_e32 v69, v75, v69
	v_exp_f32_e32 v2, v2
	v_exp_f32_e32 v4, v4
	v_and_b32_e32 v17, 64, v236
	v_pk_add_f32 v[72:73], v[14:15], v[12:13]
	v_add_f32_e32 v69, v74, v69
	v_xor_b32_e32 v16, 32, v236
	v_add_u32_e32 v17, 64, v17
	v_add_f32_e32 v69, v73, v69
	v_cmp_lt_i32_e32 vcc, v16, v17
	v_pk_add_f32 v[70:71], v[8:9], v[6:7]
	v_add_f32_e32 v69, v72, v69
	v_cndmask_b32_e32 v16, v236, v16, vcc
	v_add_f32_e32 v69, v71, v69
	v_lshlrev_b32_e32 v169, 2, v16
	v_pk_add_f32 v[16:17], v[4:5], v[2:3]
	v_add_f32_e32 v69, v70, v69
	v_add_f32_e32 v17, v17, v69
	v_add_f32_e32 v16, v16, v17
	ds_bpermute_b32 v17, v169, v16
	s_waitcnt lgkmcnt(0)
; template <int CTRL> __device__ __forceinline__ float quad_xor(float x) { return __int_as_float(__builtin_amdgcn_update_dpp(0, __float_as_int(x), CTRL, 0xF, 0xF, false)); }
; __device__ __forceinline__ void nsa_prompt_unit(Frame& F, int l, int b, int kvh, int c) {
;     ...
;         const float lt = S.l + __shfl_xor(S.l, 32), inv = lt > 0.f ? 1.f / lt : 0.f;
; #pragma unroll
;         for (int i = 0; i < 16; ++i) { s0[i] *= inv; s1[i] *= inv; }
; #pragma unroll
;         for (int i = 0; i < 16; ++i) { float a = s0[i]; a += quad_xor<0xB1>(a); a += quad_xor<0x4E>(a); float bq = s1[i]; bq += quad_xor<0xB1>(bq); bq += quad_xor<0x4E>(bq);
;             if (g == 0) { const int key = (i & 3) + 8 * (i >> 2) + 4 * h; imp[qloc * 65 + key] = a; imp[qloc * 65 + key + 32] = bq; } }
	v_add_f32_e32 v16, v16, v17
	v_div_scale_f32 v17, s[22:23], v16, v16, 1.0
	v_rcp_f32_e32 v69, v17
	s_nop 0
	v_fma_f32 v70, -v17, v69, 1.0
	v_fmac_f32_e32 v69, v70, v69
	v_div_scale_f32 v70, vcc, 1.0, v16, 1.0
	v_mul_f32_e32 v71, v70, v69
	v_fma_f32 v72, -v17, v71, v70
	v_fmac_f32_e32 v71, v72, v69
	v_fma_f32 v17, -v17, v71, v70
	v_div_fmas_f32 v17, v17, v69, v71
	v_div_fixup_f32 v17, v17, v16, 1.0
	v_cmp_lt_f32_e32 vcc, 0, v16
	v_mov_b32_e32 v70, v99
	s_nop 0
	v_cndmask_b32_e32 v16, 0, v17, vcc
	v_pk_mul_f32 v[10:11], v[10:11], v[16:17] op_sel_hi:[1,0]
	v_pk_mul_f32 v[22:23], v[22:23], v[16:17] op_sel_hi:[1,0]
	v_mul_lo_u32 v17, v1, s4
	s_add_i32 s4, 0, 0x10400
	v_cmp_eq_u32_e32 vcc, 0, v68
	v_add_u32_e32 v71, s4, v17
	v_add_f32_dpp v17, v10, v10 quad_perm:[1,0,3,2] row_mask:0xf bank_mask:0xf bound_ctrl:1
	v_mov_b32_e32 v68, v99
	v_add_f32_dpp v69, v22, v22 quad_perm:[1,0,3,2] row_mask:0xf bank_mask:0xf bound_ctrl:1
	v_lshl_add_u32 v85, v138, 2, v71
	v_mov_b32_dpp v68, v17 quad_perm:[2,3,0,1] row_mask:0xf bank_mask:0xf
	v_mov_b32_dpp v70, v69 quad_perm:[2,3,0,1] row_mask:0xf bank_mask:0xf
	s_and_saveexec_b64 s[22:23], vcc
	v_add_f32_e32 v17, v17, v68
	v_add_f32_e32 v68, v69, v70
	ds_write2_b32 v85, v17, v68 offset1:32
	s_or_b64 exec, exec, s[22:23]
	v_add_f32_dpp v17, v11, v11 quad_perm:[1,0,3,2] row_mask:0xf bank_mask:0xf bound_ctrl:1
	v_mov_b32_e32 v68, v99
	v_add_f32_dpp v69, v23, v23 quad_perm:[1,0,3,2] row_mask:0xf bank_mask:0xf bound_ctrl:1
	v_mov_b32_e32 v70, v99
	v_mov_b32_dpp v68, v17 quad_perm:[2,3,0,1] row_mask:0xf bank_mask:0xf
	s_nop 0
	v_mov_b32_dpp v70, v69 quad_perm:[2,3,0,1] row_mask:0xf bank_mask:0xf
	s_and_saveexec_b64 s[22:23], vcc
	v_add_f32_e32 v17, v17, v68
	v_add_f32_e32 v68, v69, v70
	ds_write2_b32 v85, v17, v68 offset0:1 offset1:33
	s_or_b64 exec, exec, s[22:23]
	v_mov_b32_e32 v17, v16
	v_pk_mul_f32 v[20:21], v[20:21], v[16:17]
	v_pk_mul_f32 v[24:25], v[24:25], v[16:17]
	v_mov_b32_e32 v69, v99
	v_add_f32_dpp v68, v20, v20 quad_perm:[1,0,3,2] row_mask:0xf bank_mask:0xf bound_ctrl:1
	v_add_f32_dpp v70, v24, v24 quad_perm:[1,0,3,2] row_mask:0xf bank_mask:0xf bound_ctrl:1
	v_mov_b32_e32 v71, v99
	v_mov_b32_dpp v69, v68 quad_perm:[2,3,0,1] row_mask:0xf bank_mask:0xf
	s_nop 0
	v_mov_b32_dpp v71, v70 quad_perm:[2,3,0,1] row_mask:0xf bank_mask:0xf
	s_and_saveexec_b64 s[22:23], vcc
	v_add_f32_e32 v68, v68, v69
	v_add_f32_e32 v69, v70, v71
	ds_write2_b32 v85, v68, v69 offset0:2 offset1:34
	s_or_b64 exec, exec, s[22:23]
	v_add_f32_dpp v68, v21, v21 quad_perm:[1,0,3,2] row_mask:0xf bank_mask:0xf bound_ctrl:1
	v_mov_b32_e32 v69, v99
	v_add_f32_dpp v70, v25, v25 quad_perm:[1,0,3,2] row_mask:0xf bank_mask:0xf bound_ctrl:1
	v_mov_b32_e32 v71, v99
	v_mov_b32_dpp v69, v68 quad_perm:[2,3,0,1] row_mask:0xf bank_mask:0xf
	s_nop 0
	v_mov_b32_dpp v71, v70 quad_perm:[2,3,0,1] row_mask:0xf bank_mask:0xf
	s_and_saveexec_b64 s[22:23], vcc
	v_add_f32_e32 v68, v68, v69
	v_add_f32_e32 v69, v70, v71
	ds_write2_b32 v85, v68, v69 offset0:3 offset1:35
	s_or_b64 exec, exec, s[22:23]
	v_mov_b32_e32 v68, v67
	v_mov_b32_e32 v69, v66
	v_mov_b32_e32 v66, v29
	v_mov_b32_e32 v67, v28
	v_pk_mul_f32 v[66:67], v[66:67], v[16:17]
	v_pk_mul_f32 v[28:29], v[68:69], v[16:17]
	v_mov_b32_e32 v69, v99
	v_add_f32_dpp v68, v66, v66 quad_perm:[1,0,3,2] row_mask:0xf bank_mask:0xf bound_ctrl:1
	v_add_f32_dpp v70, v28, v28 quad_perm:[1,0,3,2] row_mask:0xf bank_mask:0xf bound_ctrl:1
	v_mov_b32_e32 v71, v99
	v_mov_b32_dpp v69, v68 quad_perm:[2,3,0,1] row_mask:0xf bank_mask:0xf
	s_nop 0
	v_mov_b32_dpp v71, v70 quad_perm:[2,3,0,1] row_mask:0xf bank_mask:0xf
	s_and_saveexec_b64 s[22:23], vcc
	v_add_f32_e32 v68, v68, v69
	v_add_f32_e32 v69, v70, v71
	ds_write2_b32 v85, v68, v69 offset0:8 offset1:40
	s_or_b64 exec, exec, s[22:23]
	v_add_f32_dpp v68, v67, v67 quad_perm:[1,0,3,2] row_mask:0xf bank_mask:0xf bound_ctrl:1
	v_mov_b32_e32 v69, v99
	v_add_f32_dpp v70, v29, v29 quad_perm:[1,0,3,2] row_mask:0xf bank_mask:0xf bound_ctrl:1
	v_mov_b32_e32 v71, v99
	v_mov_b32_dpp v69, v68 quad_perm:[2,3,0,1] row_mask:0xf bank_mask:0xf
	s_nop 0
	v_mov_b32_dpp v71, v70 quad_perm:[2,3,0,1] row_mask:0xf bank_mask:0xf
	s_and_saveexec_b64 s[22:23], vcc
	v_add_f32_e32 v68, v68, v69
	v_add_f32_e32 v69, v70, v71
	ds_write2_b32 v85, v68, v69 offset0:9 offset1:41
	s_or_b64 exec, exec, s[22:23]
	v_mov_b32_e32 v68, v33
	v_mov_b32_e32 v69, v32
	v_mov_b32_e32 v32, v31
	v_mov_b32_e32 v33, v30
	v_pk_mul_f32 v[32:33], v[32:33], v[16:17]
	v_pk_mul_f32 v[30:31], v[68:69], v[16:17]
	v_mov_b32_e32 v69, v99
	v_add_f32_dpp v68, v32, v32 quad_perm:[1,0,3,2] row_mask:0xf bank_mask:0xf bound_ctrl:1
	v_add_f32_dpp v70, v30, v30 quad_perm:[1,0,3,2] row_mask:0xf bank_mask:0xf bound_ctrl:1
	v_mov_b32_e32 v71, v99
	v_mov_b32_dpp v69, v68 quad_perm:[2,3,0,1] row_mask:0xf bank_mask:0xf
	s_nop 0
	v_mov_b32_dpp v71, v70 quad_perm:[2,3,0,1] row_mask:0xf bank_mask:0xf
	s_and_saveexec_b64 s[22:23], vcc
	v_add_f32_e32 v68, v68, v69
	v_add_f32_e32 v69, v70, v71
	ds_write2_b32 v85, v68, v69 offset0:10 offset1:42
	s_or_b64 exec, exec, s[22:23]
	v_add_f32_dpp v68, v33, v33 quad_perm:[1,0,3,2] row_mask:0xf bank_mask:0xf bound_ctrl:1
	v_mov_b32_e32 v69, v99
	v_add_f32_dpp v70, v31, v31 quad_perm:[1,0,3,2] row_mask:0xf bank_mask:0xf bound_ctrl:1
	v_mov_b32_e32 v71, v99
	v_mov_b32_dpp v69, v68 quad_perm:[2,3,0,1] row_mask:0xf bank_mask:0xf
	s_nop 0
	v_mov_b32_dpp v71, v70 quad_perm:[2,3,0,1] row_mask:0xf bank_mask:0xf
	s_and_saveexec_b64 s[22:23], vcc
	v_add_f32_e32 v68, v68, v69
	v_add_f32_e32 v69, v70, v71
	ds_write2_b32 v85, v68, v69 offset0:11 offset1:43
	s_or_b64 exec, exec, s[22:23]
	v_mov_b32_e32 v70, v27
	v_mov_b32_e32 v71, v26
; template <int CTRL> __device__ __forceinline__ float quad_xor(float x) { return __int_as_float(__builtin_amdgcn_update_dpp(0, __float_as_int(x), CTRL, 0xF, 0xF, false)); }
; __device__ __forceinline__ void nsa_prompt_unit(Frame& F, int l, int b, int kvh, int c) {
;     ...
;         for (int i = 0; i < 16; ++i) { float a = s0[i]; a += quad_xor<0xB1>(a); a += quad_xor<0x4E>(a); float bq = s1[i]; bq += quad_xor<0xB1>(bq); bq += quad_xor<0x4E>(bq);
;             if (g == 0) { const int key = (i & 3) + 8 * (i >> 2) + 4 * h; imp[qloc * 65 + key] = a; imp[qloc * 65 + key + 32] = bq; } }
;         flash_pv(vf, s0, s1, S.o);
;     }
;     __syncthreads();
;     {
;         const int n = lane; const bool cand = (n >= 1) && (n <= c - 2);
;         const unsigned long long forced = 1ull | (1ull << c) | (c >= 1 ? (1ull << (c - 1)) : 0ull);
;     ...
;         __syncthreads();
;         tile_dma(kb + (size_t)tA * 4096, vt + (size_t)tA * 4096, F.lds, w, lane);
	v_mov_b32_e32 v26, v19
	v_mov_b32_e32 v27, v18
	v_pk_mul_f32 v[68:69], v[26:27], v[16:17]
	v_pk_mul_f32 v[26:27], v[70:71], v[16:17]
	v_mov_b32_e32 v19, v99
	v_add_f32_dpp v18, v68, v68 quad_perm:[1,0,3,2] row_mask:0xf bank_mask:0xf bound_ctrl:1
	v_add_f32_dpp v70, v26, v26 quad_perm:[1,0,3,2] row_mask:0xf bank_mask:0xf bound_ctrl:1
	v_mov_b32_e32 v71, v99
	v_mov_b32_dpp v19, v18 quad_perm:[2,3,0,1] row_mask:0xf bank_mask:0xf
	s_nop 0
	v_mov_b32_dpp v71, v70 quad_perm:[2,3,0,1] row_mask:0xf bank_mask:0xf
	s_and_saveexec_b64 s[22:23], vcc
	v_add_f32_e32 v18, v18, v19
	v_add_f32_e32 v19, v70, v71
	ds_write2_b32 v85, v18, v19 offset0:16 offset1:48
	s_or_b64 exec, exec, s[22:23]
	v_add_f32_dpp v18, v69, v69 quad_perm:[1,0,3,2] row_mask:0xf bank_mask:0xf bound_ctrl:1
	v_mov_b32_e32 v19, v99
	v_add_f32_dpp v70, v27, v27 quad_perm:[1,0,3,2] row_mask:0xf bank_mask:0xf bound_ctrl:1
	v_mov_b32_e32 v71, v99
	v_mov_b32_dpp v19, v18 quad_perm:[2,3,0,1] row_mask:0xf bank_mask:0xf
	s_nop 0
	v_mov_b32_dpp v71, v70 quad_perm:[2,3,0,1] row_mask:0xf bank_mask:0xf
	s_and_saveexec_b64 s[22:23], vcc
	v_add_f32_e32 v18, v18, v19
	v_add_f32_e32 v19, v70, v71
	ds_write2_b32 v85, v18, v19 offset0:17 offset1:49
	s_or_b64 exec, exec, s[22:23]
	v_mov_b32_e32 v18, v15
	v_mov_b32_e32 v19, v14
	v_mov_b32_e32 v14, v13
	v_mov_b32_e32 v15, v12
	v_pk_mul_f32 v[72:73], v[14:15], v[16:17]
	v_pk_mul_f32 v[70:71], v[18:19], v[16:17]
	v_mov_b32_e32 v13, v99
	v_add_f32_dpp v12, v72, v72 quad_perm:[1,0,3,2] row_mask:0xf bank_mask:0xf bound_ctrl:1
	v_add_f32_dpp v14, v70, v70 quad_perm:[1,0,3,2] row_mask:0xf bank_mask:0xf bound_ctrl:1
	v_mov_b32_e32 v15, v99
	v_mov_b32_dpp v13, v12 quad_perm:[2,3,0,1] row_mask:0xf bank_mask:0xf
	s_nop 0
	v_mov_b32_dpp v15, v14 quad_perm:[2,3,0,1] row_mask:0xf bank_mask:0xf
	s_and_saveexec_b64 s[22:23], vcc
	v_add_f32_e32 v12, v12, v13
	v_add_f32_e32 v13, v14, v15
	ds_write2_b32 v85, v12, v13 offset0:18 offset1:50
	s_or_b64 exec, exec, s[22:23]
	v_add_f32_dpp v12, v73, v73 quad_perm:[1,0,3,2] row_mask:0xf bank_mask:0xf bound_ctrl:1
	v_mov_b32_e32 v13, v99
	v_add_f32_dpp v14, v71, v71 quad_perm:[1,0,3,2] row_mask:0xf bank_mask:0xf bound_ctrl:1
	v_mov_b32_e32 v15, v99
	v_mov_b32_dpp v13, v12 quad_perm:[2,3,0,1] row_mask:0xf bank_mask:0xf
	s_nop 0
	v_mov_b32_dpp v15, v14 quad_perm:[2,3,0,1] row_mask:0xf bank_mask:0xf
	s_and_saveexec_b64 s[22:23], vcc
	v_add_f32_e32 v12, v12, v13
	v_add_f32_e32 v13, v14, v15
	ds_write2_b32 v85, v12, v13 offset0:19 offset1:51
	s_or_b64 exec, exec, s[22:23]
	v_mov_b32_e32 v12, v9
	v_mov_b32_e32 v13, v8
	v_mov_b32_e32 v8, v7
	v_mov_b32_e32 v9, v6
	v_pk_mul_f32 v[76:77], v[8:9], v[16:17]
	v_pk_mul_f32 v[74:75], v[12:13], v[16:17]
	v_mov_b32_e32 v7, v99
	v_add_f32_dpp v6, v76, v76 quad_perm:[1,0,3,2] row_mask:0xf bank_mask:0xf bound_ctrl:1
	v_add_f32_dpp v8, v74, v74 quad_perm:[1,0,3,2] row_mask:0xf bank_mask:0xf bound_ctrl:1
	v_mov_b32_e32 v9, v99
	v_mov_b32_dpp v7, v6 quad_perm:[2,3,0,1] row_mask:0xf bank_mask:0xf
	s_nop 0
	v_mov_b32_dpp v9, v8 quad_perm:[2,3,0,1] row_mask:0xf bank_mask:0xf
	s_and_saveexec_b64 s[22:23], vcc
	v_add_f32_e32 v6, v6, v7
	v_add_f32_e32 v7, v8, v9
	ds_write2_b32 v85, v6, v7 offset0:24 offset1:56
	s_or_b64 exec, exec, s[22:23]
	v_add_f32_dpp v6, v77, v77 quad_perm:[1,0,3,2] row_mask:0xf bank_mask:0xf bound_ctrl:1
	v_mov_b32_e32 v7, v99
	v_add_f32_dpp v8, v75, v75 quad_perm:[1,0,3,2] row_mask:0xf bank_mask:0xf bound_ctrl:1
	v_mov_b32_e32 v9, v99
	v_mov_b32_dpp v7, v6 quad_perm:[2,3,0,1] row_mask:0xf bank_mask:0xf
	s_nop 0
	v_mov_b32_dpp v9, v8 quad_perm:[2,3,0,1] row_mask:0xf bank_mask:0xf
	s_and_saveexec_b64 s[22:23], vcc
	v_add_f32_e32 v6, v6, v7
	v_add_f32_e32 v7, v8, v9
	ds_write2_b32 v85, v6, v7 offset0:25 offset1:57
	s_or_b64 exec, exec, s[22:23]
	v_mov_b32_e32 v6, v5
	v_mov_b32_e32 v7, v4
	v_mov_b32_e32 v4, v3
	v_mov_b32_e32 v5, v2
	v_pk_mul_f32 v[80:81], v[4:5], v[16:17]
	v_pk_mul_f32 v[78:79], v[6:7], v[16:17]
	v_mov_b32_e32 v3, v99
	v_add_f32_dpp v2, v80, v80 quad_perm:[1,0,3,2] row_mask:0xf bank_mask:0xf bound_ctrl:1
	v_add_f32_dpp v4, v78, v78 quad_perm:[1,0,3,2] row_mask:0xf bank_mask:0xf bound_ctrl:1
	v_mov_b32_e32 v5, v99
	v_mov_b32_dpp v3, v2 quad_perm:[2,3,0,1] row_mask:0xf bank_mask:0xf
	s_nop 0
	v_mov_b32_dpp v5, v4 quad_perm:[2,3,0,1] row_mask:0xf bank_mask:0xf
	s_and_saveexec_b64 s[22:23], vcc
	v_add_f32_e32 v2, v2, v3
	v_add_f32_e32 v3, v4, v5
	ds_write2_b32 v85, v2, v3 offset0:26 offset1:58
	s_or_b64 exec, exec, s[22:23]
	v_add_f32_dpp v2, v81, v81 quad_perm:[1,0,3,2] row_mask:0xf bank_mask:0xf bound_ctrl:1
	v_mov_b32_e32 v3, v99
	v_add_f32_dpp v4, v79, v79 quad_perm:[1,0,3,2] row_mask:0xf bank_mask:0xf bound_ctrl:1
	v_mov_b32_e32 v5, v99
	v_mov_b32_dpp v3, v2 quad_perm:[2,3,0,1] row_mask:0xf bank_mask:0xf
	s_nop 0
	v_mov_b32_dpp v5, v4 quad_perm:[2,3,0,1] row_mask:0xf bank_mask:0xf
	s_and_saveexec_b64 s[22:23], vcc
	v_add_f32_e32 v2, v2, v3
	v_add_f32_e32 v3, v4, v5
	ds_write2_b32 v85, v2, v3 offset0:27 offset1:59
	s_or_b64 exec, exec, s[22:23]
	v_cvt_pk_bf16_f32 v18, v10, v11
	v_cvt_pk_bf16_f32 v19, v20, v21
	v_cvt_pk_bf16_f32 v20, v66, v67
	v_cvt_pk_bf16_f32 v21, v32, v33
	v_cvt_pk_bf16_f32 v66, v22, v23
	v_cvt_pk_bf16_f32 v67, v24, v25
	v_mfma_f32_32x32x16_bf16 v[2:17], v[62:65], v[18:21], 0
	v_cvt_pk_bf16_f32 v62, v68, v69
	v_cvt_pk_bf16_f32 v63, v72, v73
	v_cvt_pk_bf16_f32 v64, v76, v77
	v_cvt_pk_bf16_f32 v65, v80, v81
	v_cvt_pk_bf16_f32 v68, v28, v29
	v_cvt_pk_bf16_f32 v69, v30, v31
	s_add_i32 s22, s8, -2
	v_mfma_f32_32x32x16_bf16 v[2:17], v[58:61], v[62:65], v[2:17]
	v_cvt_pk_bf16_f32 v58, v26, v27
	v_cvt_pk_bf16_f32 v59, v70, v71
	v_cvt_pk_bf16_f32 v60, v74, v75
	v_cvt_pk_bf16_f32 v61, v78, v79
	v_sub_co_u32_e64 v22, s[26:27], s8, 1
	v_cmp_ne_u32_e32 vcc, 0, v83
	v_mfma_f32_32x32x16_bf16 v[2:17], v[54:57], v[66:69], v[2:17]
	v_cmp_ge_i32_e64 s[42:43], s22, v83
	v_readfirstlane_b32 s28, v22
	s_xor_b64 s[58:59], s[44:45], -1
	s_and_b64 s[24:25], vcc, s[42:43]
	s_lshl_b64 s[22:23], 1, s8
	s_lshl_b64 s[28:29], 1, s28
	s_and_b64 s[26:27], s[26:27], exec
	v_mfma_f32_32x32x16_bf16 v[2:17], v[50:53], v[58:61], v[2:17]
	s_cselect_b32 s29, 0, s29
	s_cselect_b32 s28, 0, s28
	s_cmp_gt_u32 s8, 2
	s_cselect_b64 s[26:27], -1, 0
	s_or_b64 s[28:29], s[22:23], s[28:29]
	v_lshlrev_b32_e32 v85, 3, v83
	v_lshlrev_b32_e32 v171, 6, v84
	s_mov_b32 s37, 0
	v_lshl_add_u32 v22, v83, 2, s4
	v_cmp_eq_u32_e64 s[42:43], 0, v83
	s_or_b32 s28, s28, 1
	s_mov_b64 s[22:23], 0
	s_waitcnt lgkmcnt(0)
	s_barrier
	v_lshlrev_b32_e32 v194, 4, v83
	s_add_u32 s44, s83, s90
	s_addc_u32 s45, s81, 0
	s_add_u32 s44, s44, s40
	s_addc_u32 s45, s45, s41
	s_mov_b32 m0, s82
	s_nop 0
	global_load_lds_dwordx4 v194, s[44:45]
	s_add_u32 s44, s83, s3
	s_addc_u32 s45, s81, 0
	s_add_u32 s44, s44, s40
	s_addc_u32 s45, s45, s41
	s_mov_b32 m0, s36
	s_nop 0
	global_load_lds_dwordx4 v194, s[44:45]
	s_branch .LBB0_831

; #define NSA_POP(REM_) ((REM_) ? (t_ = sel ? __builtin_ctzll(REM_) : 63 - __builtin_clzll(REM_), (REM_) &= ~(1ull << t_), t_) : -1)
; __device__ __forceinline__ void nsa_prompt_unit(Frame& F, int l, int b, int kvh, int c) {
;     ...
;         int tA = NSA_POP(rem), tB = NSA_POP(rem);
;         int pr = 0; bool first = true;
;         __syncthreads();
;         tile_dma(kb + (size_t)tA * 4096, vt + (size_t)tA * 4096, F.lds, w, lane);
;         if (tB >= 0) tile_dma(kb + (size_t)tB * 4096, vt + (size_t)tB * 4096, F.lds + AL_SLOT, w, lane);
.LBB0_850:
	s_and_b64 s[28:29], s[66:67], exec
	s_cselect_b32 s4, 0x2bd00000, s90
	s_add_u32 s29, s83, s4
	s_addc_u32 s35, s81, 0
	s_and_b64 s[42:43], s[66:67], exec
	s_cselect_b32 s4, 0x20a00000, s3
	s_add_u32 s4, s83, s4
	s_addc_u32 s28, s81, 0
	s_ashr_i32 s23, s22, 31
	s_lshl_b64 s[42:43], s[22:23], 13
	s_add_u32 s23, s29, s42
	s_addc_u32 s37, s35, s43
	s_add_u32 s44, s4, s42
	s_addc_u32 s45, s28, s43
	s_add_u32 s42, s23, s40
	s_mov_b32 m0, s82
	s_addc_u32 s43, s37, s41
	s_waitcnt lgkmcnt(0)
	s_barrier
	s_cmp_eq_u64 s[66:67], 0
	s_cbranch_scc1 .Lselpf_a
	global_load_lds_dwordx4 v98, s[42:43]
.Lselpf_a:
	s_add_u32 s42, s44, s40
	s_addc_u32 s43, s45, s41
	s_mov_b32 m0, s36
	s_cmp_eq_u64 s[66:67], 0
	s_cbranch_scc1 .Lselpf_b
	global_load_lds_dwordx4 v98, s[42:43]
.Lselpf_b:
	s_cmp_lt_i32 s74, 0
	s_cbranch_scc1 .LBB0_852
	s_mov_b32 s75, s5
	s_lshl_b64 s[42:43], s[74:75], 13
	s_add_u32 s23, s4, s42
	s_addc_u32 s37, s28, s43
	s_add_u32 s44, s23, s40
	s_addc_u32 s45, s37, s41
	s_add_u32 s23, s29, s42
	s_addc_u32 s37, s35, s43
	s_add_u32 s42, s23, s40
	s_addc_u32 s43, s37, s41
	s_add_i32 m0, s82, 0x4000
	s_nop 0
	global_load_lds_dwordx4 v98, s[42:43]
	s_add_i32 m0, s82, 0x6000
	s_nop 0
	global_load_lds_dwordx4 v98, s[44:45]
